# scan: (nk, r_prev) pair quads stored by parity (first quads of the 16 column groups contiguous, then the second quads): the two 16-byte reads per step are bank-conflict free; one address instruction l
# speedup vs baseline: 1.0012x; 1.0012x over previous
; #define LAS __attribute__((address_space(3)))
; #define RW_LDS_WAIT(X) asm volatile("s_waitcnt lgkmcnt(0)" : "+v"(nk##X), "+v"(dd##X), "+v"(bb##X), "+v"(kp##X), "+v"(rr##X), "+v"(vv##X) :: "memory")
; DI void rwkv_scan_phase(int wv, const Params& P, LAS unsigned char* lds) {
;     ...
;         } else {
;             const int cg = lane & 15, rloc = wave * 4 + (lane >> 4);
;             f32x4 S = (f32x4){0.f, 0.f, 0.f, 0.f};
;             __syncthreads();
;             __builtin_amdgcn_s_setprio(3);
; #pragma unroll 1
;             for (int ck = 0; ck < nck; ++ck) { const int buf = ck & 1;
;                 const LAS float* sb = stg + buf * RW_T * 5 * 64 + 4 * cg; const LAS float* vb = vst + buf * RW_T * 8 + rloc; LAS float* yb = ybuf + buf * RW_T * 128 + wave * 64 + lane;
;                 const unsigned sba = (unsigned)(size_t)sb, vba = (unsigned)(size_t)vb;
;                 f32x4 nkA, ddA, bbA, kpA, rrA, nkB, ddB, bbB, kpB, rrB; float vvA, vvB;
;     ...
;                 f32x2 yacc = (f32x2){0.f, 0.f};
;                 unsigned sbt = sba, vbt = vba; LAS float* ybt = yb;
;                 RW_LDS_LOAD(A, 0); RW_LDS_WAIT(A);
; #pragma unroll 1
;                 for (int tt = 0; tt < RW_T; tt += 16) { sbt = sba + (unsigned)tt * 1280u; vbt = vba + (unsigned)tt * 32u; ybt = yb + tt * 128;
;                     RW_LDS_LOAD(B, 1); RW_STEP(A, 0); RW_LDS_WAIT(B);
;                     RW_LDS_LOAD(A, 2); RW_STEP(B, 1); RW_LDS_WAIT(A);
.LBB0_3177:
	s_waitcnt lgkmcnt(0)
	s_barrier
	s_and_saveexec_b64 s[20:21], s[2:3]
	s_xor_b64 s[20:21], exec, s[20:21]
	s_cbranch_execz .LBB0_3185
	s_barrier
	s_setprio 3
	v_add_u32_e32 v42, 0xfffec000, v63
	v_mov_b32_e32 v58, 0
	v_mov_b32_e32 v59, 0
	v_lshl_add_u32 v42, v42, 6, v45
	v_mov_b32_e32 v60, 0
	v_mov_b32_e32 v61, 0
	v_add_u32_e32 v42, 0x400, v42
	v_add_u32_e32 v62, 0x3800, v66
	s_mov_b32 s47, 0
	s_mov_b32 s42, 0
	s_lshl_b32 s40, s47, 4
	s_and_b32 s40, s40, 16
	s_mul_i32 s41, s40, 0xc00
	v_add_u32_e32 v74, s41, v45
	v_add_u32_e32 v75, s41, v42
	v_add_u32_e32 v67, s42, v62
	s_lshl_b32 s41, s40, 4
	s_add_i32 s41, s41, 0x1e000
	v_add_u32_e32 v40, s41, v45
	v_add_u32_e32 v72, 0x4000, v62
	ds_read_b128 v[0:3], v74
	ds_read_b128 v[16:19], v74 offset:256
	ds_read_b128 v[4:7], v74 offset:512
	ds_read_b128 v[12:15], v75
	ds_read_b128 v[8:11], v74 offset:768
	ds_read_b128 v[20:23], v74 offset:3072
	ds_read_b128 v[36:39], v74 offset:3328
	ds_read_b128 v[24:27], v74 offset:3584
	ds_read_b128 v[32:35], v75 offset:3072
	ds_read_b128 v[28:31], v74 offset:3840
.Lscan_chunk:
	s_waitcnt lgkmcnt(5)
	v_pk_mul_f32 v[0:1], v[58:59], v[0:1] op_sel_hi:[0,1]
	v_pk_fma_f32 v[0:1], v[58:59], v[2:3], v[0:1] op_sel:[1,0,0] op_sel_hi:[1,1,1]
	v_pk_fma_f32 v[0:1], v[60:61], v[16:17], v[0:1] op_sel_hi:[0,1,1]
	v_pk_fma_f32 v[0:1], v[60:61], v[18:19], v[0:1] op_sel:[1,0,0] op_sel_hi:[1,1,1]
	v_pk_fma_f32 v[12:13], v[58:59], v[4:5], v[12:13]
	v_pk_fma_f32 v[14:15], v[60:61], v[6:7], v[14:15]
	v_add_f32_dpp v0, v0, v0 quad_perm:[1,0,3,2] row_mask:0xf bank_mask:0xf bound_ctrl:1
	ds_read_b128 v[46:49], v74 offset:6144
	ds_read_b128 v[76:79], v74 offset:6400
	v_add_f32_dpp v0, v0, v0 quad_perm:[2,3,0,1] row_mask:0xf bank_mask:0xf bound_ctrl:1
	ds_read_b128 v[50:53], v74 offset:6656
	ds_read_b128 v[68:71], v75 offset:6144
	v_add_f32_dpp v0, v0, v0 row_half_mirror row_mask:0xf bank_mask:0xf bound_ctrl:1
	ds_read_b128 v[54:57], v74 offset:6912
	ds_write_b32 v72, v1 offset:7680
	v_add_f32_dpp v0, v0, v0 row_mirror row_mask:0xf bank_mask:0xf bound_ctrl:1
	v_pk_fma_f32 v[58:59], v[8:9], v[0:1], v[12:13] op_sel_hi:[1,0,1]
	v_pk_fma_f32 v[60:61], v[10:11], v[0:1], v[14:15] op_sel_hi:[1,0,1]
	v_mov_b32_e32 v72, v67
	s_waitcnt lgkmcnt(6)
	v_pk_mul_f32 v[20:21], v[58:59], v[20:21] op_sel_hi:[0,1]
	v_pk_fma_f32 v[20:21], v[58:59], v[22:23], v[20:21] op_sel:[1,0,0] op_sel_hi:[1,1,1]
	v_pk_fma_f32 v[20:21], v[60:61], v[36:37], v[20:21] op_sel_hi:[0,1,1]
	v_pk_fma_f32 v[20:21], v[60:61], v[38:39], v[20:21] op_sel:[1,0,0] op_sel_hi:[1,1,1]
	v_pk_fma_f32 v[32:33], v[58:59], v[24:25], v[32:33]
	v_pk_fma_f32 v[34:35], v[60:61], v[26:27], v[34:35]
	v_add_f32_dpp v20, v20, v20 quad_perm:[1,0,3,2] row_mask:0xf bank_mask:0xf bound_ctrl:1
	ds_read_b128 v[0:3], v74 offset:9216
	ds_read_b128 v[16:19], v74 offset:9472
	v_add_f32_dpp v20, v20, v20 quad_perm:[2,3,0,1] row_mask:0xf bank_mask:0xf bound_ctrl:1
	ds_read_b128 v[4:7], v74 offset:9728
	ds_read_b128 v[12:15], v75 offset:9216
	v_add_f32_dpp v20, v20, v20 row_half_mirror row_mask:0xf bank_mask:0xf bound_ctrl:1
	ds_read_b128 v[8:11], v74 offset:9984
	ds_write_b32 v72, v21
	v_add_f32_dpp v20, v20, v20 row_mirror row_mask:0xf bank_mask:0xf bound_ctrl:1
	v_pk_fma_f32 v[58:59], v[28:29], v[20:21], v[32:33] op_sel_hi:[1,0,1]
	v_pk_fma_f32 v[60:61], v[30:31], v[20:21], v[34:35] op_sel_hi:[1,0,1]
	s_waitcnt lgkmcnt(7)
	v_pk_mul_f32 v[46:47], v[58:59], v[46:47] op_sel_hi:[0,1]
	v_pk_fma_f32 v[46:47], v[58:59], v[48:49], v[46:47] op_sel:[1,0,0] op_sel_hi:[1,1,1]
	v_pk_fma_f32 v[46:47], v[60:61], v[76:77], v[46:47] op_sel_hi:[0,1,1]
	v_pk_fma_f32 v[46:47], v[60:61], v[78:79], v[46:47] op_sel:[1,0,0] op_sel_hi:[1,1,1]
	v_pk_fma_f32 v[68:69], v[58:59], v[50:51], v[68:69]
	v_pk_fma_f32 v[70:71], v[60:61], v[52:53], v[70:71]
	v_add_f32_dpp v46, v46, v46 quad_perm:[1,0,3,2] row_mask:0xf bank_mask:0xf bound_ctrl:1
	ds_read_b128 v[20:23], v74 offset:12288
	ds_read_b128 v[36:39], v74 offset:12544
	v_add_f32_dpp v46, v46, v46 quad_perm:[2,3,0,1] row_mask:0xf bank_mask:0xf bound_ctrl:1
	ds_read_b128 v[24:27], v74 offset:12800
	ds_read_b128 v[32:35], v75 offset:12288
	v_add_f32_dpp v46, v46, v46 row_half_mirror row_mask:0xf bank_mask:0xf bound_ctrl:1
	ds_read_b128 v[28:31], v74 offset:13056
	ds_write_b32 v72, v47 offset:512
	v_add_f32_dpp v46, v46, v46 row_mirror row_mask:0xf bank_mask:0xf bound_ctrl:1
	v_pk_fma_f32 v[58:59], v[54:55], v[46:47], v[68:69] op_sel_hi:[1,0,1]
	v_pk_fma_f32 v[60:61], v[56:57], v[46:47], v[70:71] op_sel_hi:[1,0,1]
	s_waitcnt lgkmcnt(7)
	v_pk_mul_f32 v[0:1], v[58:59], v[0:1] op_sel_hi:[0,1]
	v_pk_fma_f32 v[0:1], v[58:59], v[2:3], v[0:1] op_sel:[1,0,0] op_sel_hi:[1,1,1]
	v_pk_fma_f32 v[0:1], v[60:61], v[16:17], v[0:1] op_sel_hi:[0,1,1]
	v_pk_fma_f32 v[0:1], v[60:61], v[18:19], v[0:1] op_sel:[1,0,0] op_sel_hi:[1,1,1]
	v_pk_fma_f32 v[12:13], v[58:59], v[4:5], v[12:13]
	v_pk_fma_f32 v[14:15], v[60:61], v[6:7], v[14:15]
	v_add_f32_dpp v0, v0, v0 quad_perm:[1,0,3,2] row_mask:0xf bank_mask:0xf bound_ctrl:1
	ds_read_b128 v[46:49], v74 offset:15360
	ds_read_b128 v[76:79], v74 offset:15616
	v_add_f32_dpp v0, v0, v0 quad_perm:[2,3,0,1] row_mask:0xf bank_mask:0xf bound_ctrl:1
	ds_read_b128 v[50:53], v74 offset:15872
	ds_read_b128 v[68:71], v75 offset:15360
	v_add_f32_dpp v0, v0, v0 row_half_mirror row_mask:0xf bank_mask:0xf bound_ctrl:1
	ds_read_b128 v[54:57], v74 offset:16128
	ds_write_b32 v72, v1 offset:1024
	v_add_f32_dpp v0, v0, v0 row_mirror row_mask:0xf bank_mask:0xf bound_ctrl:1
	v_pk_fma_f32 v[58:59], v[8:9], v[0:1], v[12:13] op_sel_hi:[1,0,1]
	v_pk_fma_f32 v[60:61], v[10:11], v[0:1], v[14:15] op_sel_hi:[1,0,1]
	s_waitcnt lgkmcnt(7)
; #define LAS __attribute__((address_space(3)))
; #define RW_LDS_WAIT(X) asm volatile("s_waitcnt lgkmcnt(0)" : "+v"(nk##X), "+v"(dd##X), "+v"(bb##X), "+v"(kp##X), "+v"(rr##X), "+v"(vv##X) :: "memory")
; DI void rwkv_scan_phase(int wv, const Params& P, LAS unsigned char* lds) {
;     ...
;                 f32x2 yacc = (f32x2){0.f, 0.f};
;                 unsigned sbt = sba, vbt = vba; LAS float* ybt = yb;
;                 RW_LDS_LOAD(A, 0); RW_LDS_WAIT(A);
; #pragma unroll 1
;                 for (int tt = 0; tt < RW_T; tt += 16) { sbt = sba + (unsigned)tt * 1280u; vbt = vba + (unsigned)tt * 32u; ybt = yb + tt * 128;
;                     RW_LDS_LOAD(B, 1); RW_STEP(A, 0); RW_LDS_WAIT(B);
;                     RW_LDS_LOAD(A, 2); RW_STEP(B, 1); RW_LDS_WAIT(A);
;                     RW_LDS_LOAD(B, 3); RW_STEP(A, 2); RW_LDS_WAIT(B);
;                     RW_LDS_LOAD(A, 4); RW_STEP(B, 3); RW_LDS_WAIT(A);
;                     RW_LDS_LOAD(B, 5); RW_STEP(A, 4); RW_LDS_WAIT(B);
;                     RW_LDS_LOAD(A, 6); RW_STEP(B, 5); RW_LDS_WAIT(A);
;                     RW_LDS_LOAD(B, 7); RW_STEP(A, 6); RW_LDS_WAIT(B);
;                     RW_LDS_LOAD(A, 8); RW_STEP(B, 7); RW_LDS_WAIT(A);
;                     RW_LDS_LOAD(B, 9); RW_STEP(A, 8); RW_LDS_WAIT(B);
;                     RW_LDS_LOAD(A, 10); RW_STEP(B, 9); RW_LDS_WAIT(A);
;                     RW_LDS_LOAD(B, 11); RW_STEP(A, 10); RW_LDS_WAIT(B);
;                     RW_LDS_LOAD(A, 12); RW_STEP(B, 11); RW_LDS_WAIT(A);
;                     RW_LDS_LOAD(B, 13); RW_STEP(A, 12); RW_LDS_WAIT(B);
;                     RW_LDS_LOAD(A, 14); RW_STEP(B, 13); RW_LDS_WAIT(A);
;                     RW_LDS_LOAD(B, 15); RW_STEP(A, 14); RW_LDS_WAIT(B);
;                     RW_LDS_LOAD(A, 16); RW_STEP(B, 15); RW_LDS_WAIT(A);
	v_pk_mul_f32 v[20:21], v[58:59], v[20:21] op_sel_hi:[0,1]
	v_pk_fma_f32 v[20:21], v[58:59], v[22:23], v[20:21] op_sel:[1,0,0] op_sel_hi:[1,1,1]
	v_pk_fma_f32 v[20:21], v[60:61], v[36:37], v[20:21] op_sel_hi:[0,1,1]
	v_pk_fma_f32 v[20:21], v[60:61], v[38:39], v[20:21] op_sel:[1,0,0] op_sel_hi:[1,1,1]
	v_pk_fma_f32 v[32:33], v[58:59], v[24:25], v[32:33]
	v_pk_fma_f32 v[34:35], v[60:61], v[26:27], v[34:35]
	v_add_f32_dpp v20, v20, v20 quad_perm:[1,0,3,2] row_mask:0xf bank_mask:0xf bound_ctrl:1
	ds_read_b128 v[0:3], v74 offset:18432
	ds_read_b128 v[16:19], v74 offset:18688
	v_add_f32_dpp v20, v20, v20 quad_perm:[2,3,0,1] row_mask:0xf bank_mask:0xf bound_ctrl:1
	ds_read_b128 v[4:7], v74 offset:18944
	ds_read_b128 v[12:15], v75 offset:18432
	v_add_f32_dpp v20, v20, v20 row_half_mirror row_mask:0xf bank_mask:0xf bound_ctrl:1
	ds_read_b128 v[8:11], v74 offset:19200
	ds_write_b32 v72, v21 offset:1536
	v_add_f32_dpp v20, v20, v20 row_mirror row_mask:0xf bank_mask:0xf bound_ctrl:1
	v_pk_fma_f32 v[58:59], v[28:29], v[20:21], v[32:33] op_sel_hi:[1,0,1]
	v_pk_fma_f32 v[60:61], v[30:31], v[20:21], v[34:35] op_sel_hi:[1,0,1]
	s_waitcnt lgkmcnt(7)
	v_pk_mul_f32 v[46:47], v[58:59], v[46:47] op_sel_hi:[0,1]
	v_pk_fma_f32 v[46:47], v[58:59], v[48:49], v[46:47] op_sel:[1,0,0] op_sel_hi:[1,1,1]
	v_pk_fma_f32 v[46:47], v[60:61], v[76:77], v[46:47] op_sel_hi:[0,1,1]
	v_pk_fma_f32 v[46:47], v[60:61], v[78:79], v[46:47] op_sel:[1,0,0] op_sel_hi:[1,1,1]
	v_pk_fma_f32 v[68:69], v[58:59], v[50:51], v[68:69]
	v_pk_fma_f32 v[70:71], v[60:61], v[52:53], v[70:71]
	v_add_f32_dpp v46, v46, v46 quad_perm:[1,0,3,2] row_mask:0xf bank_mask:0xf bound_ctrl:1
	ds_read_b128 v[20:23], v74 offset:21504
	ds_read_b128 v[36:39], v74 offset:21760
	v_add_f32_dpp v46, v46, v46 quad_perm:[2,3,0,1] row_mask:0xf bank_mask:0xf bound_ctrl:1
	ds_read_b128 v[24:27], v74 offset:22016
	ds_read_b128 v[32:35], v75 offset:21504
	v_add_f32_dpp v46, v46, v46 row_half_mirror row_mask:0xf bank_mask:0xf bound_ctrl:1
	ds_read_b128 v[28:31], v74 offset:22272
	ds_write_b32 v72, v47 offset:2048
	v_add_f32_dpp v46, v46, v46 row_mirror row_mask:0xf bank_mask:0xf bound_ctrl:1
	v_pk_fma_f32 v[58:59], v[54:55], v[46:47], v[68:69] op_sel_hi:[1,0,1]
	v_pk_fma_f32 v[60:61], v[56:57], v[46:47], v[70:71] op_sel_hi:[1,0,1]
	s_waitcnt lgkmcnt(7)
	v_pk_mul_f32 v[0:1], v[58:59], v[0:1] op_sel_hi:[0,1]
	v_pk_fma_f32 v[0:1], v[58:59], v[2:3], v[0:1] op_sel:[1,0,0] op_sel_hi:[1,1,1]
	v_pk_fma_f32 v[0:1], v[60:61], v[16:17], v[0:1] op_sel_hi:[0,1,1]
	v_pk_fma_f32 v[0:1], v[60:61], v[18:19], v[0:1] op_sel:[1,0,0] op_sel_hi:[1,1,1]
	v_pk_fma_f32 v[12:13], v[58:59], v[4:5], v[12:13]
	v_pk_fma_f32 v[14:15], v[60:61], v[6:7], v[14:15]
	v_add_f32_dpp v0, v0, v0 quad_perm:[1,0,3,2] row_mask:0xf bank_mask:0xf bound_ctrl:1
	ds_read_b128 v[46:49], v74 offset:24576
	ds_read_b128 v[76:79], v74 offset:24832
	v_add_f32_dpp v0, v0, v0 quad_perm:[2,3,0,1] row_mask:0xf bank_mask:0xf bound_ctrl:1
	ds_read_b128 v[50:53], v74 offset:25088
	ds_read_b128 v[68:71], v75 offset:24576
	v_add_f32_dpp v0, v0, v0 row_half_mirror row_mask:0xf bank_mask:0xf bound_ctrl:1
	ds_read_b128 v[54:57], v74 offset:25344
	ds_write_b32 v72, v1 offset:2560
	v_add_f32_dpp v0, v0, v0 row_mirror row_mask:0xf bank_mask:0xf bound_ctrl:1
	v_pk_fma_f32 v[58:59], v[8:9], v[0:1], v[12:13] op_sel_hi:[1,0,1]
	v_pk_fma_f32 v[60:61], v[10:11], v[0:1], v[14:15] op_sel_hi:[1,0,1]
	s_waitcnt lgkmcnt(7)
	v_pk_mul_f32 v[20:21], v[58:59], v[20:21] op_sel_hi:[0,1]
	v_pk_fma_f32 v[20:21], v[58:59], v[22:23], v[20:21] op_sel:[1,0,0] op_sel_hi:[1,1,1]
	v_pk_fma_f32 v[20:21], v[60:61], v[36:37], v[20:21] op_sel_hi:[0,1,1]
	v_pk_fma_f32 v[20:21], v[60:61], v[38:39], v[20:21] op_sel:[1,0,0] op_sel_hi:[1,1,1]
	v_pk_fma_f32 v[32:33], v[58:59], v[24:25], v[32:33]
	v_pk_fma_f32 v[34:35], v[60:61], v[26:27], v[34:35]
	v_add_f32_dpp v20, v20, v20 quad_perm:[1,0,3,2] row_mask:0xf bank_mask:0xf bound_ctrl:1
	ds_read_b128 v[0:3], v74 offset:27648
	ds_read_b128 v[16:19], v74 offset:27904
	v_add_f32_dpp v20, v20, v20 quad_perm:[2,3,0,1] row_mask:0xf bank_mask:0xf bound_ctrl:1
	ds_read_b128 v[4:7], v74 offset:28160
	ds_read_b128 v[12:15], v75 offset:27648
	v_add_f32_dpp v20, v20, v20 row_half_mirror row_mask:0xf bank_mask:0xf bound_ctrl:1
	ds_read_b128 v[8:11], v74 offset:28416
	ds_write_b32 v72, v21 offset:3072
	v_add_f32_dpp v20, v20, v20 row_mirror row_mask:0xf bank_mask:0xf bound_ctrl:1
	v_pk_fma_f32 v[58:59], v[28:29], v[20:21], v[32:33] op_sel_hi:[1,0,1]
	v_pk_fma_f32 v[60:61], v[30:31], v[20:21], v[34:35] op_sel_hi:[1,0,1]
	s_waitcnt lgkmcnt(7)
	v_pk_mul_f32 v[46:47], v[58:59], v[46:47] op_sel_hi:[0,1]
	v_pk_fma_f32 v[46:47], v[58:59], v[48:49], v[46:47] op_sel:[1,0,0] op_sel_hi:[1,1,1]
	v_pk_fma_f32 v[46:47], v[60:61], v[76:77], v[46:47] op_sel_hi:[0,1,1]
	v_pk_fma_f32 v[46:47], v[60:61], v[78:79], v[46:47] op_sel:[1,0,0] op_sel_hi:[1,1,1]
	v_pk_fma_f32 v[68:69], v[58:59], v[50:51], v[68:69]
	v_pk_fma_f32 v[70:71], v[60:61], v[52:53], v[70:71]
	v_add_f32_dpp v46, v46, v46 quad_perm:[1,0,3,2] row_mask:0xf bank_mask:0xf bound_ctrl:1
	ds_read_b128 v[20:23], v74 offset:30720
	ds_read_b128 v[36:39], v74 offset:30976
	v_add_f32_dpp v46, v46, v46 quad_perm:[2,3,0,1] row_mask:0xf bank_mask:0xf bound_ctrl:1
	ds_read_b128 v[24:27], v74 offset:31232
	ds_read_b128 v[32:35], v75 offset:30720
	v_add_f32_dpp v46, v46, v46 row_half_mirror row_mask:0xf bank_mask:0xf bound_ctrl:1
	ds_read_b128 v[28:31], v74 offset:31488
	ds_write_b32 v72, v47 offset:3584
	v_add_f32_dpp v46, v46, v46 row_mirror row_mask:0xf bank_mask:0xf bound_ctrl:1
	v_pk_fma_f32 v[58:59], v[54:55], v[46:47], v[68:69] op_sel_hi:[1,0,1]
	v_pk_fma_f32 v[60:61], v[56:57], v[46:47], v[70:71] op_sel_hi:[1,0,1]
	s_waitcnt lgkmcnt(7)
; #define LAS __attribute__((address_space(3)))
; #define RW_LDS_WAIT(X) asm volatile("s_waitcnt lgkmcnt(0)" : "+v"(nk##X), "+v"(dd##X), "+v"(bb##X), "+v"(kp##X), "+v"(rr##X), "+v"(vv##X) :: "memory")
; DI void rwkv_scan_phase(int wv, const Params& P, LAS unsigned char* lds) {
;     ...
;                 f32x2 yacc = (f32x2){0.f, 0.f};
;                 unsigned sbt = sba, vbt = vba; LAS float* ybt = yb;
;                 RW_LDS_LOAD(A, 0); RW_LDS_WAIT(A);
; #pragma unroll 1
;                 for (int tt = 0; tt < RW_T; tt += 16) { sbt = sba + (unsigned)tt * 1280u; vbt = vba + (unsigned)tt * 32u; ybt = yb + tt * 128;
;                     RW_LDS_LOAD(B, 1); RW_STEP(A, 0); RW_LDS_WAIT(B);
;                     RW_LDS_LOAD(A, 2); RW_STEP(B, 1); RW_LDS_WAIT(A);
;                     RW_LDS_LOAD(B, 3); RW_STEP(A, 2); RW_LDS_WAIT(B);
;                     RW_LDS_LOAD(A, 4); RW_STEP(B, 3); RW_LDS_WAIT(A);
;                     RW_LDS_LOAD(B, 5); RW_STEP(A, 4); RW_LDS_WAIT(B);
;                     RW_LDS_LOAD(A, 6); RW_STEP(B, 5); RW_LDS_WAIT(A);
;                     RW_LDS_LOAD(B, 7); RW_STEP(A, 6); RW_LDS_WAIT(B);
;                     RW_LDS_LOAD(A, 8); RW_STEP(B, 7); RW_LDS_WAIT(A);
;                     RW_LDS_LOAD(B, 9); RW_STEP(A, 8); RW_LDS_WAIT(B);
;                     RW_LDS_LOAD(A, 10); RW_STEP(B, 9); RW_LDS_WAIT(A);
;                     RW_LDS_LOAD(B, 11); RW_STEP(A, 10); RW_LDS_WAIT(B);
;                     RW_LDS_LOAD(A, 12); RW_STEP(B, 11); RW_LDS_WAIT(A);
;                     RW_LDS_LOAD(B, 13); RW_STEP(A, 12); RW_LDS_WAIT(B);
;                     RW_LDS_LOAD(A, 14); RW_STEP(B, 13); RW_LDS_WAIT(A);
;                     RW_LDS_LOAD(B, 15); RW_STEP(A, 14); RW_LDS_WAIT(B);
;                     RW_LDS_LOAD(A, 16); RW_STEP(B, 15); RW_LDS_WAIT(A);
;                 }
;                 yb[(RW_T - 1) * 128] = yacc[0] + yacc[1];
;     ...
;                 __syncthreads();
	v_pk_mul_f32 v[0:1], v[58:59], v[0:1] op_sel_hi:[0,1]
	v_pk_fma_f32 v[0:1], v[58:59], v[2:3], v[0:1] op_sel:[1,0,0] op_sel_hi:[1,1,1]
	v_pk_fma_f32 v[0:1], v[60:61], v[16:17], v[0:1] op_sel_hi:[0,1,1]
	v_pk_fma_f32 v[0:1], v[60:61], v[18:19], v[0:1] op_sel:[1,0,0] op_sel_hi:[1,1,1]
	v_pk_fma_f32 v[12:13], v[58:59], v[4:5], v[12:13]
	v_pk_fma_f32 v[14:15], v[60:61], v[6:7], v[14:15]
	v_add_f32_dpp v0, v0, v0 quad_perm:[1,0,3,2] row_mask:0xf bank_mask:0xf bound_ctrl:1
	ds_read_b128 v[46:49], v74 offset:33792
	ds_read_b128 v[76:79], v74 offset:34048
	v_add_f32_dpp v0, v0, v0 quad_perm:[2,3,0,1] row_mask:0xf bank_mask:0xf bound_ctrl:1
	ds_read_b128 v[50:53], v74 offset:34304
	ds_read_b128 v[68:71], v75 offset:33792
	v_add_f32_dpp v0, v0, v0 row_half_mirror row_mask:0xf bank_mask:0xf bound_ctrl:1
	ds_read_b128 v[54:57], v74 offset:34560
	ds_write_b32 v72, v1 offset:4096
	v_add_f32_dpp v0, v0, v0 row_mirror row_mask:0xf bank_mask:0xf bound_ctrl:1
	v_pk_fma_f32 v[58:59], v[8:9], v[0:1], v[12:13] op_sel_hi:[1,0,1]
	v_pk_fma_f32 v[60:61], v[10:11], v[0:1], v[14:15] op_sel_hi:[1,0,1]
	s_waitcnt lgkmcnt(7)
	v_pk_mul_f32 v[20:21], v[58:59], v[20:21] op_sel_hi:[0,1]
	v_pk_fma_f32 v[20:21], v[58:59], v[22:23], v[20:21] op_sel:[1,0,0] op_sel_hi:[1,1,1]
	v_pk_fma_f32 v[20:21], v[60:61], v[36:37], v[20:21] op_sel_hi:[0,1,1]
	v_pk_fma_f32 v[20:21], v[60:61], v[38:39], v[20:21] op_sel:[1,0,0] op_sel_hi:[1,1,1]
	v_pk_fma_f32 v[32:33], v[58:59], v[24:25], v[32:33]
	v_pk_fma_f32 v[34:35], v[60:61], v[26:27], v[34:35]
	v_add_f32_dpp v20, v20, v20 quad_perm:[1,0,3,2] row_mask:0xf bank_mask:0xf bound_ctrl:1
	ds_read_b128 v[0:3], v74 offset:36864
	ds_read_b128 v[16:19], v74 offset:37120
	v_add_f32_dpp v20, v20, v20 quad_perm:[2,3,0,1] row_mask:0xf bank_mask:0xf bound_ctrl:1
	ds_read_b128 v[4:7], v74 offset:37376
	ds_read_b128 v[12:15], v75 offset:36864
	v_add_f32_dpp v20, v20, v20 row_half_mirror row_mask:0xf bank_mask:0xf bound_ctrl:1
	ds_read_b128 v[8:11], v74 offset:37632
	ds_write_b32 v72, v21 offset:4608
	v_add_f32_dpp v20, v20, v20 row_mirror row_mask:0xf bank_mask:0xf bound_ctrl:1
	v_pk_fma_f32 v[58:59], v[28:29], v[20:21], v[32:33] op_sel_hi:[1,0,1]
	v_pk_fma_f32 v[60:61], v[30:31], v[20:21], v[34:35] op_sel_hi:[1,0,1]
	s_waitcnt lgkmcnt(7)
	v_pk_mul_f32 v[46:47], v[58:59], v[46:47] op_sel_hi:[0,1]
	v_pk_fma_f32 v[46:47], v[58:59], v[48:49], v[46:47] op_sel:[1,0,0] op_sel_hi:[1,1,1]
	v_pk_fma_f32 v[46:47], v[60:61], v[76:77], v[46:47] op_sel_hi:[0,1,1]
	v_pk_fma_f32 v[46:47], v[60:61], v[78:79], v[46:47] op_sel:[1,0,0] op_sel_hi:[1,1,1]
	v_pk_fma_f32 v[68:69], v[58:59], v[50:51], v[68:69]
	v_pk_fma_f32 v[70:71], v[60:61], v[52:53], v[70:71]
	v_add_f32_dpp v46, v46, v46 quad_perm:[1,0,3,2] row_mask:0xf bank_mask:0xf bound_ctrl:1
	ds_read_b128 v[20:23], v74 offset:39936
	ds_read_b128 v[36:39], v74 offset:40192
	v_add_f32_dpp v46, v46, v46 quad_perm:[2,3,0,1] row_mask:0xf bank_mask:0xf bound_ctrl:1
	ds_read_b128 v[24:27], v74 offset:40448
	ds_read_b128 v[32:35], v75 offset:39936
	v_add_f32_dpp v46, v46, v46 row_half_mirror row_mask:0xf bank_mask:0xf bound_ctrl:1
	ds_read_b128 v[28:31], v74 offset:40704
	ds_write_b32 v72, v47 offset:5120
	v_add_f32_dpp v46, v46, v46 row_mirror row_mask:0xf bank_mask:0xf bound_ctrl:1
	v_pk_fma_f32 v[58:59], v[54:55], v[46:47], v[68:69] op_sel_hi:[1,0,1]
	v_pk_fma_f32 v[60:61], v[56:57], v[46:47], v[70:71] op_sel_hi:[1,0,1]
	s_waitcnt lgkmcnt(7)
	v_pk_mul_f32 v[0:1], v[58:59], v[0:1] op_sel_hi:[0,1]
	v_pk_fma_f32 v[0:1], v[58:59], v[2:3], v[0:1] op_sel:[1,0,0] op_sel_hi:[1,1,1]
	v_pk_fma_f32 v[0:1], v[60:61], v[16:17], v[0:1] op_sel_hi:[0,1,1]
	v_pk_fma_f32 v[0:1], v[60:61], v[18:19], v[0:1] op_sel:[1,0,0] op_sel_hi:[1,1,1]
	v_pk_fma_f32 v[12:13], v[58:59], v[4:5], v[12:13]
	v_pk_fma_f32 v[14:15], v[60:61], v[6:7], v[14:15]
	v_add_f32_dpp v0, v0, v0 quad_perm:[1,0,3,2] row_mask:0xf bank_mask:0xf bound_ctrl:1
	ds_read_b128 v[46:49], v74 offset:43008
	ds_read_b128 v[76:79], v74 offset:43264
	v_add_f32_dpp v0, v0, v0 quad_perm:[2,3,0,1] row_mask:0xf bank_mask:0xf bound_ctrl:1
	ds_read_b128 v[50:53], v74 offset:43520
	ds_read_b128 v[68:71], v75 offset:43008
	v_add_f32_dpp v0, v0, v0 row_half_mirror row_mask:0xf bank_mask:0xf bound_ctrl:1
	ds_read_b128 v[54:57], v74 offset:43776
	ds_write_b32 v72, v1 offset:5632
	v_add_f32_dpp v0, v0, v0 row_mirror row_mask:0xf bank_mask:0xf bound_ctrl:1
	v_pk_fma_f32 v[58:59], v[8:9], v[0:1], v[12:13] op_sel_hi:[1,0,1]
	v_pk_fma_f32 v[60:61], v[10:11], v[0:1], v[14:15] op_sel_hi:[1,0,1]
	s_waitcnt lgkmcnt(7)
	v_pk_mul_f32 v[20:21], v[58:59], v[20:21] op_sel_hi:[0,1]
	v_pk_fma_f32 v[20:21], v[58:59], v[22:23], v[20:21] op_sel:[1,0,0] op_sel_hi:[1,1,1]
	v_pk_fma_f32 v[20:21], v[60:61], v[36:37], v[20:21] op_sel_hi:[0,1,1]
	v_pk_fma_f32 v[20:21], v[60:61], v[38:39], v[20:21] op_sel:[1,0,0] op_sel_hi:[1,1,1]
	v_pk_fma_f32 v[32:33], v[58:59], v[24:25], v[32:33]
	v_pk_fma_f32 v[34:35], v[60:61], v[26:27], v[34:35]
	v_add_f32_dpp v20, v20, v20 quad_perm:[1,0,3,2] row_mask:0xf bank_mask:0xf bound_ctrl:1
	ds_read_b128 v[0:3], v74 offset:46080
	ds_read_b128 v[16:19], v74 offset:46336
	v_add_f32_dpp v20, v20, v20 quad_perm:[2,3,0,1] row_mask:0xf bank_mask:0xf bound_ctrl:1
	ds_read_b128 v[4:7], v74 offset:46592
	ds_read_b128 v[12:15], v75 offset:46080
	v_add_f32_dpp v20, v20, v20 row_half_mirror row_mask:0xf bank_mask:0xf bound_ctrl:1
	ds_read_b128 v[8:11], v74 offset:46848
	ds_write_b32 v72, v21 offset:6144
	v_add_f32_dpp v20, v20, v20 row_mirror row_mask:0xf bank_mask:0xf bound_ctrl:1
	v_pk_fma_f32 v[58:59], v[28:29], v[20:21], v[32:33] op_sel_hi:[1,0,1]
	v_pk_fma_f32 v[60:61], v[30:31], v[20:21], v[34:35] op_sel_hi:[1,0,1]
	s_waitcnt lgkmcnt(7)
	v_pk_mul_f32 v[46:47], v[58:59], v[46:47] op_sel_hi:[0,1]
	v_pk_fma_f32 v[46:47], v[58:59], v[48:49], v[46:47] op_sel:[1,0,0] op_sel_hi:[1,1,1]
	v_pk_fma_f32 v[46:47], v[60:61], v[76:77], v[46:47] op_sel_hi:[0,1,1]
	v_pk_fma_f32 v[46:47], v[60:61], v[78:79], v[46:47] op_sel:[1,0,0] op_sel_hi:[1,1,1]
	v_pk_fma_f32 v[68:69], v[58:59], v[50:51], v[68:69]
	v_pk_fma_f32 v[70:71], v[60:61], v[52:53], v[70:71]
	v_add_f32_dpp v46, v46, v46 quad_perm:[1,0,3,2] row_mask:0xf bank_mask:0xf bound_ctrl:1
	s_add_i32 s47, s47, 1
	ds_write_b32 v72, v47 offset:6656
	v_add_f32_dpp v46, v46, v46 quad_perm:[2,3,0,1] row_mask:0xf bank_mask:0xf bound_ctrl:1
	s_add_i32 s42, s42, 0x2000
	s_cmp_eq_u32 s42, 0x6000
	v_add_f32_dpp v46, v46, v46 row_half_mirror row_mask:0xf bank_mask:0xf bound_ctrl:1
	s_cselect_b32 s42, 0, s42
	s_lshl_b32 s40, s47, 4
	v_add_f32_dpp v46, v46, v46 row_mirror row_mask:0xf bank_mask:0xf bound_ctrl:1
	v_pk_fma_f32 v[58:59], v[54:55], v[46:47], v[68:69] op_sel_hi:[1,0,1]
	v_pk_fma_f32 v[60:61], v[56:57], v[46:47], v[70:71] op_sel_hi:[1,0,1]
	s_waitcnt lgkmcnt(0)
	s_barrier
; #define RW_LDS_WAIT(X) asm volatile("s_waitcnt lgkmcnt(0)" : "+v"(nk##X), "+v"(dd##X), "+v"(bb##X), "+v"(kp##X), "+v"(rr##X), "+v"(vv##X) :: "memory")
; DI void rwkv_scan_phase(int wv, const Params& P, LAS unsigned char* lds) {
;     ...
;                 for (int tt = 0; tt < RW_T; tt += 16) { sbt = sba + (unsigned)tt * 1280u; vbt = vba + (unsigned)tt * 32u; ybt = yb + tt * 128;
;                     RW_LDS_LOAD(B, 1); RW_STEP(A, 0); RW_LDS_WAIT(B);
;                     RW_LDS_LOAD(A, 2); RW_STEP(B, 1); RW_LDS_WAIT(A);
;                     RW_LDS_LOAD(B, 3); RW_STEP(A, 2); RW_LDS_WAIT(B);
;                     RW_LDS_LOAD(A, 4); RW_STEP(B, 3); RW_LDS_WAIT(A);
;                     RW_LDS_LOAD(B, 5); RW_STEP(A, 4); RW_LDS_WAIT(B);
;                     RW_LDS_LOAD(A, 6); RW_STEP(B, 5); RW_LDS_WAIT(A);
;                     RW_LDS_LOAD(B, 7); RW_STEP(A, 6); RW_LDS_WAIT(B);
;                     RW_LDS_LOAD(A, 8); RW_STEP(B, 7); RW_LDS_WAIT(A);
;                     RW_LDS_LOAD(B, 9); RW_STEP(A, 8); RW_LDS_WAIT(B);
;                     RW_LDS_LOAD(A, 10); RW_STEP(B, 9); RW_LDS_WAIT(A);
;                     RW_LDS_LOAD(B, 11); RW_STEP(A, 10); RW_LDS_WAIT(B);
;                     RW_LDS_LOAD(A, 12); RW_STEP(B, 11); RW_LDS_WAIT(A);
;                     RW_LDS_LOAD(B, 13); RW_STEP(A, 12); RW_LDS_WAIT(B);
;                     RW_LDS_LOAD(A, 14); RW_STEP(B, 13); RW_LDS_WAIT(A);
;                     RW_LDS_LOAD(B, 15); RW_STEP(A, 14); RW_LDS_WAIT(B);
;                     RW_LDS_LOAD(A, 16); RW_STEP(B, 15); RW_LDS_WAIT(A);
;                 }
;                 yb[(RW_T - 1) * 128] = yacc[0] + yacc[1];
;     ...
;                 __syncthreads();
	v_pk_mul_f32 v[0:1], v[58:59], v[0:1] op_sel_hi:[0,1]
	v_pk_fma_f32 v[0:1], v[58:59], v[2:3], v[0:1] op_sel:[1,0,0] op_sel_hi:[1,1,1]
	v_pk_fma_f32 v[0:1], v[60:61], v[16:17], v[0:1] op_sel_hi:[0,1,1]
	v_pk_fma_f32 v[0:1], v[60:61], v[18:19], v[0:1] op_sel:[1,0,0] op_sel_hi:[1,1,1]
	v_pk_fma_f32 v[12:13], v[58:59], v[4:5], v[12:13]
	v_pk_fma_f32 v[14:15], v[60:61], v[6:7], v[14:15]
	v_add_f32_dpp v0, v0, v0 quad_perm:[1,0,3,2] row_mask:0xf bank_mask:0xf bound_ctrl:1
	ds_write_b32 v72, v1 offset:7168
	s_and_b32 s40, s40, 16
	v_add_f32_dpp v0, v0, v0 quad_perm:[2,3,0,1] row_mask:0xf bank_mask:0xf bound_ctrl:1
	s_mul_i32 s41, s40, 0xc00
	v_add_u32_e32 v74, s41, v45
	v_add_f32_dpp v0, v0, v0 row_half_mirror row_mask:0xf bank_mask:0xf bound_ctrl:1
	v_add_u32_e32 v75, s41, v42
	v_add_u32_e32 v67, s42, v62
	v_add_f32_dpp v0, v0, v0 row_mirror row_mask:0xf bank_mask:0xf bound_ctrl:1
	v_pk_fma_f32 v[58:59], v[8:9], v[0:1], v[12:13] op_sel_hi:[1,0,1]
	v_pk_fma_f32 v[60:61], v[10:11], v[0:1], v[14:15] op_sel_hi:[1,0,1]
	s_lshl_b32 s41, s40, 4
	s_add_i32 s41, s41, 0x1e000
	v_add_u32_e32 v40, s41, v45
	s_cmpk_eq_i32 s47, 0x200
	ds_read_b128 v[0:3], v74
	ds_read_b128 v[16:19], v74 offset:256
	ds_read_b128 v[4:7], v74 offset:512
	ds_read_b128 v[12:15], v75
	ds_read_b128 v[8:11], v74 offset:768
	ds_read_b128 v[20:23], v74 offset:3072
	ds_read_b128 v[36:39], v74 offset:3328
	ds_read_b128 v[24:27], v74 offset:3584
	ds_read_b128 v[32:35], v75 offset:3072
	ds_read_b128 v[28:31], v74 offset:3840
	s_cbranch_scc0 .Lscan_chunk
	v_add_u32_e32 v40, 0x1e100, v45
	ds_read_b128 v[20:23], v40
	s_waitcnt lgkmcnt(0)
	v_pk_mul_f32 v[64:65], v[20:21], v[58:59]
	v_pk_fma_f32 v[64:65], v[22:23], v[60:61], v[64:65]
	s_nop 0
	v_add_f32_e32 v64, v64, v65
	ds_write_b32 v72, v64 offset:7680
	s_waitcnt lgkmcnt(0)
	s_barrier

; DI void rwkv_scan_phase(int wv, const Params& P, LAS unsigned char* lds) {
;     ...
;         if (wave >= 2) {
;             const int ch = h * 64 + lane;
;             const float kkw = P.in[35][ch], kaw = P.in[36][ch], rkw = P.in[37][ch];
;             const int hf = lane >> 5, c2 = lane & 31, chp = h * 64 + 2 * c2;
;             const f32x2 kkw2 = *(const f32x2*)(P.in[35] + chp), kaw2 = *(const f32x2*)(P.in[36] + chp), rkw2 = *(const f32x2*)(P.in[37] + chp);
;             unsigned gk[3], ga[3], gr[3], gl[3]; float gv[3];
;     ...
;             RW_LOADG(0)
; #pragma unroll 1
;             for (int ck = -1; ck <= nck; ++ck) {
;                 {
;                     if (ck >= 1) { const LAS float* yb = ybuf + ((ck - 1) & 1) * RW_T * 128;
; #pragma unroll 2
;                         for (int it = pw; it < 64; it += 6) { const float y = row16_sum(yb[it * 64 + lane]);
;                             const float y0 = __builtin_bit_cast(float, __builtin_amdgcn_readlane(__builtin_bit_cast(int, y), 0)), y1 = __builtin_bit_cast(float, __builtin_amdgcn_readlane(__builtin_bit_cast(int, y), 16)),
;                                         y2 = __builtin_bit_cast(float, __builtin_amdgcn_readlane(__builtin_bit_cast(int, y), 32)), y3 = __builtin_bit_cast(float, __builtin_amdgcn_readlane(__builtin_bit_cast(int, y), 48));
;                             if (lane == 0) { u32x2 w; w.x = pk2(y0, y1); w.y = pk2(y2, y3); *(u32x2*)(YS + ((size_t)b * SEQ + (ck - 1) * RW_T + (it >> 1)) * 1024 + h * 64 + rg * 8 + (it & 1) * 4) = w; } } }
;                     if (ck + 1 < nck) { const int cn = ck + 1, buf = cn & 1;
; #pragma unroll
;                         for (int i = 0; i < 3; ++i) { const int pp = pw + 6 * i; if (pp < 16) { const int tt = 2 * pp + hf; const size_t row = (size_t)b * SEQ + cn * RW_T + tt;
;                             const f32x2 k = {bflo(gk[i]), bfhi(gk[i])}, a = {bflo(ga[i]), bfhi(ga[i])}, r = {bflo(gr[i]), bfhi(gr[i])};
;                             const h16x2 lh = __builtin_bit_cast(h16x2, gl[i]);
;                             const f32x2 kr = k * kkw2, kp = k * ((a - 1.f) * kaw2 + 1.f);
;                             const float sp = kr[0] * kr[0] + kr[1] * kr[1], rp = r[0] * kp[0] * rkw2[0] + r[1] * kp[1] * rkw2[1];
;                             const bool odd = lane & 1;
;                             float red = (odd ? rp : sp) + dpp_f<0xB1>(odd ? sp : rp);
.LBB0_3185:
	s_andn2_saveexec_b64 s[40:41], s[20:21]
	s_cbranch_execz .LBB0_3174
	v_readfirstlane_b32 s55, v41
	s_and_b32 s66, s55, 2
	s_cmp_lg_u32 s66, 0
	s_cbranch_scc1 .Lprod_flusher
	s_lshr_b32 s66, s55, 1
	s_and_b32 s55, s55, 1
	s_or_b32 s55, s55, s66
	s_and_b32 s67, s46, 7
	s_bfe_u32 s59, s46, 0x40003
	s_lshr_b32 s60, s46, 7
	s_lshl_b32 s60, s60, 13
	s_lshl_b32 s66, s55, 2
	s_add_i32 s60, s60, s66
	v_mbcnt_lo_u32_b32 v0, -1, 0
	v_mbcnt_hi_u32_b32 v0, -1, v0
	v_and_b32_e32 v1, 31, v0
	v_lshrrev_b32_e32 v31, 5, v0
	s_lshl_b32 s61, s59, 6
	v_lshl_add_u32 v32, v1, 1, s61
	v_lshlrev_b32_e32 v33, 2, v32
	global_load_dwordx2 v[4:5], v33, s[24:25]
	global_load_dwordx2 v[6:7], v33, s[26:27]
	global_load_dwordx2 v[8:9], v33, s[38:39]
	v_add_u32_e32 v34, s60, v31
	v_lshlrev_b32_e32 v35, 11, v34
	v_lshl_add_u32 v12, v32, 1, v35
	v_add_u32_e32 v13, 0x1000, v12
	s_lshl_b32 s66, s55, 2
	v_add_u32_e32 v37, s66, v31
	v_mul_u32_u24_e32 v2, 0xc00, v37
	v_lshl_add_u32 v2, v1, 3, v2
	s_lshl_b32 s66, s59, 2
	v_lshl_add_u32 v10, v34, 6, s66
	v_or_b32_e32 v38, s67, v1
	v_cmp_eq_u32_e64 s[42:43], 0, v38
	v_mov_b32_e32 v52, v2
	v_lshlrev_b32_e32 v53, 3, v1
	v_sub_u32_e32 v53, v52, v53
	v_and_b32_e32 v38, 1, v1
	v_lshl_add_u32 v53, v38, 8, v53
	v_lshrrev_b32_e32 v38, 1, v1
	v_lshl_add_u32 v53, v38, 4, v53
	v_mov_b32_e32 v54, 0x1e000
	v_lshl_add_u32 v54, v1, 3, v54
	v_add_u32_e32 v55, 0xc000, v2
	v_add_u32_e32 v56, 0xc000, v53
	v_add_u32_e32 v57, 0x100, v54
	s_mov_b32 s57, -1
	s_mov_b32 s67, 0
	s_waitcnt vmcnt(0)
	v_add_u32_e32 v14, s67, v12
	v_add_u32_e32 v15, s67, v13
	global_load_dword v44, v14, s[28:29]
	global_load_dword v48, v15, s[28:29]
	global_load_dword v45, v14, s[34:35]
	global_load_dword v49, v15, s[34:35]
	global_load_dword v46, v14, s[22:23]
	global_load_dword v50, v15, s[22:23]
	global_load_dword v47, v14, s[36:37]
	global_load_dword v51, v15, s[36:37]
	global_load_dword v0, v14, s[22:23] offset:-2048
	global_load_dword v40, v15, s[22:23] offset:-2048
	s_mov_b32 s67, 0x8000
	v_add_u32_e32 v14, s67, v12
	v_add_u32_e32 v15, s67, v13
	global_load_dword v24, v14, s[28:29]
	global_load_dword v28, v15, s[28:29]
	global_load_dword v25, v14, s[34:35]
	global_load_dword v29, v15, s[34:35]
	global_load_dword v26, v14, s[22:23]
	global_load_dword v30, v15, s[22:23]
	global_load_dword v27, v14, s[36:37]
	global_load_dword v31, v15, s[36:37]
	global_load_dword v3, v14, s[22:23] offset:-2048
	global_load_dword v43, v15, s[22:23] offset:-2048
